# same as previous plus pe-bias loop batched 32 k-steps per wait (bit-exact)
# speedup vs baseline: 1.0293x; 1.0002x over previous
; #define LAS __attribute__((address_space(3)))
; DI unsigned char* WSP(const Params& p) { GAS unsigned char* w = (GAS unsigned char*)p.ws; asm volatile("" : "+s"(w)); return (unsigned char*)w; }
; DI const float* INP(const Params& p, int i) { asm volatile("" : "+s"(i)); return (const float*)(GAS const float*)p.in[i]; }
; __global__ void __launch_bounds__(512, 2) hymba_fwd(Params p) {
;     ...
;             for (int it = bid; it < 4; it += G) { const int L = it >> 1, kv = it & 1;
;                 const float* pe = INP(p, kv ? 10 : 9) + (size_t)L * 4096; const float* w1 = INP(p, kv ? 13 : 11) + (size_t)L * 4096 * 128;
;                 const int j = tid & 127, part = tid >> 7; float s = 0.f;
;                 for (int k = part * 1024; k < part * 1024 + 1024; ++k) s += pe[k] * w1[(size_t)k * 128 + j];
;                 LAS float* red = (LAS float*)lds + 8 * 64 * 33;
;                 red[tid] = s; __syncthreads();
;                 if (tid < 128) ((float*)(WSP(p) + WS_PEB))[(L * 2 + kv) * 128 + tid] = red[tid] + red[tid + 128] + red[tid + 256] + red[tid + 384];
;                 __syncthreads(); }
.LBB0_825:
	global_load_dwordx4 v[14:17], v[4:5], off
	global_load_dwordx4 v[18:21], v[4:5], off offset:16
	global_load_dwordx4 v[22:25], v[4:5], off offset:32
	global_load_dwordx4 v[26:29], v[4:5], off offset:48
	global_load_dwordx4 v[30:33], v[4:5], off offset:64
	global_load_dwordx4 v[34:37], v[4:5], off offset:80
	global_load_dwordx4 v[38:41], v[4:5], off offset:96
	global_load_dwordx4 v[42:45], v[4:5], off offset:112
	v_add_co_u32_e32 v80, vcc, 0x2000, v6
	s_nop 1
	v_addc_co_u32_e32 v81, vcc, 0, v7, vcc
	global_load_dword v46, v[6:7], off offset:-4096
	global_load_dword v47, v[6:7], off offset:-3584
	global_load_dword v48, v[6:7], off offset:-3072
	global_load_dword v49, v[6:7], off offset:-2560
	global_load_dword v50, v[6:7], off offset:-2048
	global_load_dword v51, v[6:7], off offset:-1536
	global_load_dword v52, v[6:7], off offset:-1024
	global_load_dword v53, v[6:7], off offset:-512
	global_load_dword v54, v[6:7], off offset:0
	global_load_dword v55, v[6:7], off offset:512
	global_load_dword v56, v[6:7], off offset:1024
	global_load_dword v57, v[6:7], off offset:1536
	global_load_dword v58, v[6:7], off offset:2048
	global_load_dword v59, v[6:7], off offset:2560
	global_load_dword v60, v[6:7], off offset:3072
	global_load_dword v61, v[6:7], off offset:3584
	global_load_dword v62, v[80:81], off offset:-4096
	global_load_dword v63, v[80:81], off offset:-3584
	global_load_dword v65, v[80:81], off offset:-3072
	global_load_dword v66, v[80:81], off offset:-2560
	global_load_dword v67, v[80:81], off offset:-2048
	global_load_dword v68, v[80:81], off offset:-1536
	global_load_dword v69, v[80:81], off offset:-1024
	global_load_dword v70, v[80:81], off offset:-512
	global_load_dword v71, v[80:81], off offset:0
	global_load_dword v72, v[80:81], off offset:512
	global_load_dword v73, v[80:81], off offset:1024
	global_load_dword v74, v[80:81], off offset:1536
	global_load_dword v75, v[80:81], off offset:2048
	global_load_dword v76, v[80:81], off offset:2560
	global_load_dword v77, v[80:81], off offset:3072
	global_load_dword v78, v[80:81], off offset:3584
	v_add_u32_e32 v13, 32, v13
	s_mov_b64 s[8:9], 0x80
	v_cmp_ge_i32_e32 vcc, v13, v10
	v_lshl_add_u64 v[4:5], v[4:5], 0, s[8:9]
	s_mov_b64 s[8:9], 0x4000
	v_lshl_add_u64 v[6:7], v[6:7], 0, s[8:9]
	s_or_b64 s[4:5], vcc, s[4:5]
	s_waitcnt vmcnt(31)
	v_fmac_f32_e32 v12, v14, v46
	s_waitcnt vmcnt(30)
	v_fmac_f32_e32 v12, v15, v47
	s_waitcnt vmcnt(29)
	v_fmac_f32_e32 v12, v16, v48
	s_waitcnt vmcnt(28)
	v_fmac_f32_e32 v12, v17, v49
	s_waitcnt vmcnt(27)
	v_fmac_f32_e32 v12, v18, v50
	s_waitcnt vmcnt(26)
	v_fmac_f32_e32 v12, v19, v51
	s_waitcnt vmcnt(25)
	v_fmac_f32_e32 v12, v20, v52
	s_waitcnt vmcnt(24)
	v_fmac_f32_e32 v12, v21, v53
	s_waitcnt vmcnt(23)
	v_fmac_f32_e32 v12, v22, v54
	s_waitcnt vmcnt(22)
	v_fmac_f32_e32 v12, v23, v55
	s_waitcnt vmcnt(21)
	v_fmac_f32_e32 v12, v24, v56
	s_waitcnt vmcnt(20)
	v_fmac_f32_e32 v12, v25, v57
	s_waitcnt vmcnt(19)
	v_fmac_f32_e32 v12, v26, v58
	s_waitcnt vmcnt(18)
	v_fmac_f32_e32 v12, v27, v59
	s_waitcnt vmcnt(17)
	v_fmac_f32_e32 v12, v28, v60
	s_waitcnt vmcnt(16)
	v_fmac_f32_e32 v12, v29, v61
	s_waitcnt vmcnt(15)
	v_fmac_f32_e32 v12, v30, v62
	s_waitcnt vmcnt(14)
	v_fmac_f32_e32 v12, v31, v63
	s_waitcnt vmcnt(13)
	v_fmac_f32_e32 v12, v32, v65
	s_waitcnt vmcnt(12)
	v_fmac_f32_e32 v12, v33, v66
	s_waitcnt vmcnt(11)
	v_fmac_f32_e32 v12, v34, v67
	s_waitcnt vmcnt(10)
	v_fmac_f32_e32 v12, v35, v68
	s_waitcnt vmcnt(9)
	v_fmac_f32_e32 v12, v36, v69
	s_waitcnt vmcnt(8)
	v_fmac_f32_e32 v12, v37, v70
	s_waitcnt vmcnt(7)
	v_fmac_f32_e32 v12, v38, v71
	s_waitcnt vmcnt(6)
	v_fmac_f32_e32 v12, v39, v72
	s_waitcnt vmcnt(5)
	v_fmac_f32_e32 v12, v40, v73
	s_waitcnt vmcnt(4)
	v_fmac_f32_e32 v12, v41, v74
	s_waitcnt vmcnt(3)
	v_fmac_f32_e32 v12, v42, v75
	s_waitcnt vmcnt(2)
	v_fmac_f32_e32 v12, v43, v76
	s_waitcnt vmcnt(1)
	v_fmac_f32_e32 v12, v44, v77
	s_waitcnt vmcnt(0)
	v_fmac_f32_e32 v12, v45, v78
	s_andn2_b64 exec, exec, s[4:5]
	s_cbranch_execnz .LBB0_825
	s_or_b64 exec, exec, s[4:5]
	ds_write_b32 v9, v12
	s_waitcnt lgkmcnt(0)
	s_barrier
	s_and_saveexec_b64 s[4:5], s[6:7]
	s_cbranch_execz .LBB0_823
	ds_read2st64_b32 v[4:5], v9 offset1:2
	ds_read2st64_b32 v[6:7], v9 offset0:4 offset1:6
	v_lshl_add_u32 v12, s2, 7, v8
	s_mov_b64 s[8:9], s[28:29]
	v_ashrrev_i32_e32 v13, 31, v12
	s_waitcnt lgkmcnt(1)
	v_add_f32_e32 v4, v4, v5
	s_waitcnt lgkmcnt(0)
	v_add_f32_e32 v4, v4, v6
	v_add_f32_e32 v6, v4, v7
	v_lshl_add_u64 v[4:5], v[12:13], 2, s[8:9]
	v_add_co_u32_e32 v4, vcc, 0x3a6a2000, v4
	s_nop 1
	v_addc_co_u32_e32 v5, vcc, 0, v5, vcc
	global_store_dword v[4:5], v6, off
	s_branch .LBB0_823
